# step3 + per-XCD K-tile rotation of the P1 GEMM K-loop (each XCD starts its K sweep at a different tile; wrap handled by a tile counter)
# speedup vs baseline: 1.0093x; 1.0004x over previous
.LBB0_296:
	s_add_u32 s60, s74, 0x13b00000
	s_addc_u32 s61, s75, 0
	s_add_u32 s50, s74, 0xfb00000
	s_addc_u32 s51, s75, 0
	s_andn2_b64 vcc, exec, s[4:5]
	s_cbranch_vccnz .LBB0_381
	v_bfe_i32 v2, v12, 27, 1
	v_lshlrev_b32_e32 v0, 4, v12
	v_lshrrev_b32_e32 v2, 22, v2
	v_add_u32_e32 v2, v0, v2
	v_and_b32_e32 v2, 0xfffffc00, v2
	v_sub_u32_e32 v2, v0, v2
	v_ashrrev_i32_e32 v1, 31, v12
	v_lshrrev_b32_e32 v3, 4, v2
	v_lshrrev_b32_e32 v1, 26, v1
	v_bitop3_b32 v2, v3, v2, 32 bitop3:0x6c
	v_add_u32_e32 v1, v12, v1
	v_ashrrev_i32_e32 v4, 31, v2
	v_ashrrev_i32_e32 v1, 6, v1
	v_lshrrev_b32_e32 v4, 26, v4
	v_lshlrev_b32_e32 v3, 3, v1
	v_add_u32_e32 v4, v2, v4
	v_and_b32_e32 v3, -16, v3
	v_ashrrev_i32_e32 v5, 6, v4
	v_lshlrev_b32_e32 v1, 5, v1
	v_add_u32_e32 v3, v5, v3
	v_and_b32_e32 v13, 32, v1
	v_and_b32_e32 v1, 0xc0, v4
	v_sub_u32_e32 v1, v2, v1
	v_mov_b32_e32 v2, 1
	v_lshlrev_b32_e32 v4, 1, v3
	v_lshrrev_b32_e32 v6, 2, v3
	v_and_b32_e32 v5, 3, v5
	s_mov_b32 s1, 0x7fffffe0
	v_ashrrev_i16_sdwa v1, v2, sext(v1) dst_sel:DWORD dst_unused:UNUSED_PAD src0_sel:DWORD src1_sel:BYTE_0
	v_and_b32_e32 v4, 24, v4
	v_and_b32_e32 v6, 4, v6
	v_and_or_b32 v5, v3, s1, v5
	v_bfe_i32 v14, v1, 0, 16
	v_or3_b32 v4, v5, v6, v4
	v_add_u32_e32 v1, v13, v14
	v_mul_lo_u32 v15, v3, s0
	v_mul_lo_u32 v3, v4, s0
	v_add_u32_e32 v0, 0x2000, v0
	v_lshrrev_b32_e32 v252, 3, v220
	v_bfe_u32 v253, v220, 4, 2
	v_bfe_u32 v254, v220, 6, 1
	v_lshl_or_b32 v253, v254, 2, v253
	v_and_b32_e32 v254, 7, v220
	v_xor_b32_e32 v253, v254, v253
	v_lshlrev_b32_e32 v253, 4, v253
	v_and_b32_e32 v254, 32, v252
	v_bfe_u32 v255, v252, 2, 2
	v_lshl_or_b32 v254, v255, 3, v254
	v_bfe_u32 v255, v252, 4, 1
	v_lshl_or_b32 v254, v255, 2, v254
	v_and_b32_e32 v255, 3, v252
	v_or_b32_e32 v254, v254, v255
	v_mul_u32_u24_e32 v254, 0x1000, v254
	v_add_u32_e32 v254, v254, v253
	v_add_u32_e32 v255, 0x40000, v254
	v_mul_u32_u24_e32 v252, 0x1000, v252
	v_add_u32_e32 v252, v252, v253
	v_add_u32_e32 v253, 0x40000, v252
	v_mov_b32_e32 v128, v252
	v_mov_b32_e32 v130, v254
	v_ashrrev_i32_e32 v1, 31, v0
	v_lshrrev_b32_e32 v1, 22, v1
	v_add_u32_e32 v1, v0, v1
	v_ashrrev_i32_e32 v1, 10, v1
	v_mul_i32_i24_e32 v3, 0x400, v1
	v_sub_u32_e32 v0, v0, v3
	v_lshrrev_b32_e32 v3, 4, v0
	v_bitop3_b32 v0, v3, v0, 32 bitop3:0x6c
	v_ashrrev_i32_e32 v4, 31, v0
	v_lshrrev_b32_e32 v4, 26, v4
	v_lshlrev_b32_e32 v3, 3, v1
	v_add_u32_e32 v4, v0, v4
	v_and_b32_e32 v3, -16, v3
	v_ashrrev_i32_e32 v5, 6, v4
	v_lshlrev_b32_e32 v1, 5, v1
	s_add_u32 s30, s74, 0x700000
	v_add_u32_e32 v3, v5, v3
	v_and_b32_e32 v16, 32, v1
	v_and_b32_e32 v1, 0xc0, v4
	v_and_b32_e32 v4, 3, v5
	s_addc_u32 s31, s75, 0
	s_and_b32 s95, s2, 7
	s_lshl_b32 s95, s95, 2
	s_lshl_b32 s94, s95, 7
	s_add_u32 s30, s30, s94
	s_addc_u32 s31, s31, 0
	v_and_or_b32 v4, v3, s1, v4
	s_ashr_i32 s1, s0, 31
	s_lshl_b64 s[12:13], s[0:1], 9
	s_ashr_i32 s7, s29, 31
	s_mul_i32 s7, s12, s7
	s_mul_hi_u32 s8, s12, s29
	s_ashr_i32 s14, s28, 31
	s_add_i32 s7, s8, s7
	s_lshr_b64 s[8:9], s[0:1], 23
	s_mul_i32 s14, s12, s14
	s_mul_hi_u32 s15, s12, s28
	s_ashr_i32 s4, s6, 6
	s_mul_i32 s9, s8, s29
	s_add_i32 s14, s15, s14
	s_mul_i32 s8, s8, s28
	v_sub_u32_e32 v0, v0, v1
	s_ashr_i32 s5, s6, 8
	s_lshl_b64 s[10:11], s[0:1], 8
	s_lshl_b32 s34, s4, 10
	s_add_i32 s7, s7, s9
	s_add_i32 s14, s14, s8
	s_mul_i32 s8, s12, s28
	v_ashrrev_i16_sdwa v0, v2, sext(v0) dst_sel:DWORD dst_unused:UNUSED_PAD src0_sel:DWORD src1_sel:BYTE_0
	v_lshlrev_b32_e32 v1, 1, v3
	v_lshrrev_b32_e32 v2, 2, v3
	s_add_u32 s22, s30, s8
	v_and_b32_e32 v1, 24, v1
	v_and_b32_e32 v2, 4, v2
	s_addc_u32 s23, s31, s14
	s_add_i32 s35, s34, 0
	v_bfe_i32 v17, v0, 0, 16
	v_or3_b32 v1, v4, v2, v1
	s_add_i32 m0, s35, 0x10000
	v_add_u32_e32 v0, v16, v17
	v_mul_lo_u32 v1, v1, s0
	global_load_lds_dwordx4 v130, s[22:23]
	s_add_i32 m0, s35, 0x12000
	v_mov_b32_e32 v134, v255
	s_add_u32 s14, s22, s10
	global_load_lds_dwordx4 v134, s[22:23]
	s_addc_u32 s15, s23, s11
	s_add_i32 m0, s35, 0x14000
	s_mul_i32 s9, s12, s29
	global_load_lds_dwordx4 v130, s[14:15]
	s_add_i32 m0, s35, 0x16000
	s_add_u32 s8, s50, s9
	s_addc_u32 s9, s51, s7
	s_lshl_b32 s94, s95, 7
	s_add_u32 s8, s8, s94
	s_addc_u32 s9, s9, 0
	s_add_i32 s36, s35, 0x2000
	v_mul_lo_u32 v18, v3, s0
	global_load_lds_dwordx4 v134, s[14:15]
	s_mov_b32 m0, s35
	s_add_u32 s16, s8, s10
	v_mov_b32_e32 v132, v253
	global_load_lds_dwordx4 v128, s[8:9]
	s_mov_b32 m0, s36
	s_addc_u32 s17, s9, s11
	s_add_i32 s37, s35, 0x4000
	global_load_lds_dwordx4 v132, s[8:9]
	s_mov_b32 m0, s37
	s_add_i32 s38, s35, 0x6000
	global_load_lds_dwordx4 v128, s[16:17]
	s_mov_b32 m0, s38
	v_mov_b32_e32 v137, 0
	global_load_lds_dwordx4 v132, s[16:17]
	v_mov_b32_e32 v131, v137
	v_mov_b32_e32 v135, v137
	v_mov_b32_e32 v129, v137
	v_mov_b32_e32 v133, v137
	s_cmp_eq_u32 s5, 1
	s_mov_b32 s39, 0
	v_lshl_add_u64 v[8:9], s[22:23], 0, v[130:131]
	v_lshl_add_u64 v[4:5], s[22:23], 0, v[134:135]
	v_lshl_add_u64 v[2:3], s[14:15], 0, v[130:131]
	v_lshl_add_u64 v[0:1], s[14:15], 0, v[134:135]
	v_lshl_add_u64 v[6:7], s[8:9], 0, v[128:129]
	s_cselect_b64 s[14:15], -1, 0
	s_cmp_lg_u32 s5, 1
	v_lshl_add_u64 v[10:11], s[8:9], 0, v[132:133]
	s_cbranch_scc1 .LBB0_299
	s_barrier

.LBB0_304:
	s_nop 0
	v_cndmask_b32_e64 v0, 0, 1, s[0:1]
	v_cmp_ne_u32_e64 s[6:7], 1, v0
	s_andn2_b64 vcc, exec, s[0:1]
	s_mov_b64 s[0:1], s[8:9]
	s_cbranch_vccnz .LBB0_306
	s_ashr_i32 s0, s80, 31
	s_mul_hi_u32 s1, s12, s80
	s_mul_i32 s0, s12, s0
	s_add_i32 s0, s1, s0
	s_mul_i32 s1, s13, s80
	s_add_i32 s1, s0, s1
	s_mul_i32 s0, s12, s80
	s_add_u32 s0, s50, s0
	s_addc_u32 s1, s51, s1
	s_lshl_b32 s94, s95, 7
	s_add_u32 s0, s0, s94
	s_addc_u32 s1, s1, 0

.LBB0_308:
	v_mov_b32_e32 v127, 0
	s_and_b64 vcc, exec, s[4:5]
	v_mov_b32_e32 v126, v127
	v_mov_b32_e32 v125, v127
	v_mov_b32_e32 v124, v127
	v_mov_b32_e32 v123, v127
	v_mov_b32_e32 v122, v127
	v_mov_b32_e32 v121, v127
	v_mov_b32_e32 v120, v127
	v_mov_b32_e32 v111, v127
	v_mov_b32_e32 v110, v127
	v_mov_b32_e32 v109, v127
	v_mov_b32_e32 v108, v127
	v_mov_b32_e32 v107, v127
	v_mov_b32_e32 v106, v127
	v_mov_b32_e32 v105, v127
	v_mov_b32_e32 v104, v127
	v_mov_b32_e32 v95, v127
	v_mov_b32_e32 v94, v127
	v_mov_b32_e32 v93, v127
	v_mov_b32_e32 v92, v127
	v_mov_b32_e32 v91, v127
	v_mov_b32_e32 v90, v127
	v_mov_b32_e32 v89, v127
	v_mov_b32_e32 v88, v127
	v_mov_b32_e32 v79, v127
	v_mov_b32_e32 v78, v127
	v_mov_b32_e32 v77, v127
	v_mov_b32_e32 v76, v127
	v_mov_b32_e32 v75, v127
	v_mov_b32_e32 v74, v127
	v_mov_b32_e32 v73, v127
	v_mov_b32_e32 v72, v127
	v_mov_b32_e32 v119, v127
	v_mov_b32_e32 v118, v127
	v_mov_b32_e32 v117, v127
	v_mov_b32_e32 v116, v127
	v_mov_b32_e32 v115, v127
	v_mov_b32_e32 v114, v127
	v_mov_b32_e32 v113, v127
	v_mov_b32_e32 v112, v127
	v_mov_b32_e32 v103, v127
	v_mov_b32_e32 v102, v127
	v_mov_b32_e32 v101, v127
	v_mov_b32_e32 v100, v127
	v_mov_b32_e32 v99, v127
	v_mov_b32_e32 v98, v127
	v_mov_b32_e32 v97, v127
	v_mov_b32_e32 v96, v127
	v_mov_b32_e32 v87, v127
	v_mov_b32_e32 v86, v127
	v_mov_b32_e32 v85, v127
	v_mov_b32_e32 v84, v127
	v_mov_b32_e32 v83, v127
	v_mov_b32_e32 v82, v127
	v_mov_b32_e32 v81, v127
	v_mov_b32_e32 v80, v127
	v_mov_b32_e32 v71, v127
	v_mov_b32_e32 v70, v127
	v_mov_b32_e32 v69, v127
	v_mov_b32_e32 v68, v127
	v_mov_b32_e32 v67, v127
	v_mov_b32_e32 v66, v127
	v_mov_b32_e32 v65, v127
	v_mov_b32_e32 v64, v127
	v_mov_b32_e32 v63, v127
	v_mov_b32_e32 v62, v127
	v_mov_b32_e32 v61, v127
	v_mov_b32_e32 v60, v127
	v_mov_b32_e32 v59, v127
	v_mov_b32_e32 v58, v127
	v_mov_b32_e32 v57, v127
	v_mov_b32_e32 v56, v127
	v_mov_b32_e32 v47, v127
	v_mov_b32_e32 v46, v127
	v_mov_b32_e32 v45, v127
	v_mov_b32_e32 v44, v127
	v_mov_b32_e32 v43, v127
	v_mov_b32_e32 v42, v127
	v_mov_b32_e32 v41, v127
	v_mov_b32_e32 v40, v127
	v_mov_b32_e32 v31, v127
	v_mov_b32_e32 v30, v127
	v_mov_b32_e32 v29, v127
	v_mov_b32_e32 v28, v127
	v_mov_b32_e32 v27, v127
	v_mov_b32_e32 v26, v127
	v_mov_b32_e32 v25, v127
	v_mov_b32_e32 v24, v127
	v_mov_b32_e32 v15, v127
	v_mov_b32_e32 v14, v127
	v_mov_b32_e32 v13, v127
	v_mov_b32_e32 v12, v127
	v_mov_b32_e32 v11, v127
	v_mov_b32_e32 v10, v127
	v_mov_b32_e32 v9, v127
	v_mov_b32_e32 v8, v127
	v_mov_b32_e32 v55, v127
	v_mov_b32_e32 v54, v127
	v_mov_b32_e32 v53, v127
	v_mov_b32_e32 v52, v127
	v_mov_b32_e32 v51, v127
	v_mov_b32_e32 v50, v127
	v_mov_b32_e32 v49, v127
	v_mov_b32_e32 v48, v127
	v_mov_b32_e32 v39, v127
	v_mov_b32_e32 v38, v127
	v_mov_b32_e32 v37, v127
	v_mov_b32_e32 v36, v127
	v_mov_b32_e32 v35, v127
	v_mov_b32_e32 v34, v127
	v_mov_b32_e32 v33, v127
	v_mov_b32_e32 v32, v127
	v_mov_b32_e32 v23, v127
	v_mov_b32_e32 v22, v127
	v_mov_b32_e32 v21, v127
	v_mov_b32_e32 v20, v127
	v_mov_b32_e32 v19, v127
	v_mov_b32_e32 v18, v127
	v_mov_b32_e32 v17, v127
	v_mov_b32_e32 v16, v127
	v_mov_b32_e32 v7, v127
	v_mov_b32_e32 v6, v127
	v_mov_b32_e32 v5, v127
	v_mov_b32_e32 v4, v127
	v_mov_b32_e32 v3, v127
	v_mov_b32_e32 v2, v127
	v_mov_b32_e32 v1, v127
	v_mov_b32_e32 v0, v127
	s_cbranch_vccnz .LBB0_311
	s_mov_b32 s93, s95
	s_add_u32 s8, s8, 0x80
	s_addc_u32 s9, s9, 0
	s_add_u32 s24, s22, 0x100
	v_mov_b32_e32 v0, 0
	s_addc_u32 s25, s23, 0
	s_mov_b32 s22, 0
	v_mov_b32_e32 v1, v0
	v_mov_b32_e32 v2, v0
	v_mov_b32_e32 v3, v0
	v_mov_b32_e32 v4, v0
	v_mov_b32_e32 v5, v0
	v_mov_b32_e32 v6, v0
	v_mov_b32_e32 v7, v0
	v_mov_b32_e32 v16, v0
	v_mov_b32_e32 v17, v0
	v_mov_b32_e32 v18, v0
	v_mov_b32_e32 v19, v0
	v_mov_b32_e32 v20, v0
	v_mov_b32_e32 v21, v0
	v_mov_b32_e32 v22, v0
	v_mov_b32_e32 v23, v0
	v_mov_b32_e32 v32, v0
	v_mov_b32_e32 v33, v0
	v_mov_b32_e32 v34, v0
	v_mov_b32_e32 v35, v0
	v_mov_b32_e32 v36, v0
	v_mov_b32_e32 v37, v0
	v_mov_b32_e32 v38, v0
	v_mov_b32_e32 v39, v0
	v_mov_b32_e32 v48, v0
	v_mov_b32_e32 v49, v0
	v_mov_b32_e32 v50, v0
	v_mov_b32_e32 v51, v0
	v_mov_b32_e32 v52, v0
	v_mov_b32_e32 v53, v0
	v_mov_b32_e32 v54, v0
	v_mov_b32_e32 v55, v0
	v_mov_b32_e32 v8, v0
	v_mov_b32_e32 v9, v0
	v_mov_b32_e32 v10, v0
	v_mov_b32_e32 v11, v0
	v_mov_b32_e32 v12, v0
	v_mov_b32_e32 v13, v0
	v_mov_b32_e32 v14, v0
	v_mov_b32_e32 v15, v0
	v_mov_b32_e32 v24, v0
	v_mov_b32_e32 v25, v0
	v_mov_b32_e32 v26, v0
	v_mov_b32_e32 v27, v0
	v_mov_b32_e32 v28, v0
	v_mov_b32_e32 v29, v0
	v_mov_b32_e32 v30, v0
	v_mov_b32_e32 v31, v0
	v_mov_b32_e32 v40, v0
	v_mov_b32_e32 v41, v0
	v_mov_b32_e32 v42, v0
	v_mov_b32_e32 v43, v0
	v_mov_b32_e32 v44, v0
	v_mov_b32_e32 v45, v0
	v_mov_b32_e32 v46, v0
	v_mov_b32_e32 v47, v0
	v_mov_b32_e32 v56, v0
	v_mov_b32_e32 v57, v0
	v_mov_b32_e32 v58, v0
	v_mov_b32_e32 v59, v0
	v_mov_b32_e32 v60, v0
	v_mov_b32_e32 v61, v0
	v_mov_b32_e32 v62, v0
	v_mov_b32_e32 v63, v0
	v_mov_b32_e32 v64, v0
	v_mov_b32_e32 v65, v0
	v_mov_b32_e32 v66, v0
	v_mov_b32_e32 v67, v0
	v_mov_b32_e32 v68, v0
	v_mov_b32_e32 v69, v0
	v_mov_b32_e32 v70, v0
	v_mov_b32_e32 v71, v0
	v_mov_b32_e32 v80, v0
	v_mov_b32_e32 v81, v0
	v_mov_b32_e32 v82, v0
	v_mov_b32_e32 v83, v0
	v_mov_b32_e32 v84, v0
	v_mov_b32_e32 v85, v0
	v_mov_b32_e32 v86, v0
	v_mov_b32_e32 v87, v0
	v_mov_b32_e32 v96, v0
	v_mov_b32_e32 v97, v0
	v_mov_b32_e32 v98, v0
	v_mov_b32_e32 v99, v0
	v_mov_b32_e32 v100, v0
	v_mov_b32_e32 v101, v0
	v_mov_b32_e32 v102, v0
	v_mov_b32_e32 v103, v0
	v_mov_b32_e32 v112, v0
	v_mov_b32_e32 v113, v0
	v_mov_b32_e32 v114, v0
	v_mov_b32_e32 v115, v0
	v_mov_b32_e32 v116, v0
	v_mov_b32_e32 v117, v0
	v_mov_b32_e32 v118, v0
	v_mov_b32_e32 v119, v0
	v_mov_b32_e32 v72, v0
	v_mov_b32_e32 v73, v0
	v_mov_b32_e32 v74, v0
	v_mov_b32_e32 v75, v0
	v_mov_b32_e32 v76, v0
	v_mov_b32_e32 v77, v0
	v_mov_b32_e32 v78, v0
	v_mov_b32_e32 v79, v0
	v_mov_b32_e32 v88, v0
	v_mov_b32_e32 v89, v0
	v_mov_b32_e32 v90, v0
	v_mov_b32_e32 v91, v0
	v_mov_b32_e32 v92, v0
	v_mov_b32_e32 v93, v0
	v_mov_b32_e32 v94, v0
	v_mov_b32_e32 v95, v0
	v_mov_b32_e32 v104, v0
	v_mov_b32_e32 v105, v0
	v_mov_b32_e32 v106, v0
	v_mov_b32_e32 v107, v0
	v_mov_b32_e32 v108, v0
	v_mov_b32_e32 v109, v0
	v_mov_b32_e32 v110, v0
	v_mov_b32_e32 v111, v0
	v_mov_b32_e32 v120, v0
	v_mov_b32_e32 v121, v0
	v_mov_b32_e32 v122, v0
	v_mov_b32_e32 v123, v0
	v_mov_b32_e32 v124, v0
	v_mov_b32_e32 v125, v0
	v_mov_b32_e32 v126, v0
	v_mov_b32_e32 v127, v0
.LBB0_310:
	ds_read_b128 v[148:151], v160
	ds_read_b128 v[164:167], v253
	ds_read_b128 v[168:171], v160 offset:2048
	ds_read_b128 v[172:175], v253 offset:2048
	ds_read_b128 v[176:179], v161
	ds_read_b128 v[180:183], v254
	ds_read_b128 v[184:187], v161 offset:2048
	ds_read_b128 v[188:191], v254 offset:2048
	s_add_i32 s26, s22, 2
	s_add_u32 s27, s8, 0x80
	s_addc_u32 s23, s9, 0
	s_cmp_eq_u32 s93, 30
	s_cselect_b32 s94, 0x1000, 0
	s_sub_u32 s27, s27, s94
	s_subb_u32 s23, s23, 0
	s_cmp_eq_u32 s45, s22
	s_cselect_b32 s22, s0, s27
	s_cselect_b32 s23, s1, s23
	s_cselect_b32 s85, s21, s25
	s_cselect_b32 s84, s20, s24
	v_lshl_add_u64 v[152:153], s[8:9], 0, v[140:141]
	s_add_i32 m0, s35, 0xc000
	ds_read_b128 v[192:195], v162
	ds_read_b128 v[196:199], v252
	ds_read_b128 v[200:203], v162 offset:2048
	ds_read_b128 v[204:207], v252 offset:2048
	ds_read_b128 v[208:211], v162 offset:4096
	ds_read_b128 v[212:215], v252 offset:4096
	ds_read_b128 v[216:219], v162 offset:6144
	ds_read_b128 v[222:225], v252 offset:6144
	global_load_lds_dwordx4 v[152:153], off
	v_lshl_add_u64 v[152:153], s[8:9], 0, v[142:143]
	s_add_i32 m0, s35, 0xe000
	s_nop 0
	global_load_lds_dwordx4 v[152:153], off
	s_waitcnt vmcnt(8)
	s_waitcnt lgkmcnt(0)
	s_setprio 1
	s_barrier
	v_mfma_f32_16x16x32_bf16 v[124:127], v[148:151], v[192:195], v[124:127]
	v_mfma_f32_16x16x32_bf16 v[120:123], v[168:171], v[192:195], v[120:123]
	v_mfma_f32_16x16x32_bf16 v[108:111], v[148:151], v[200:203], v[108:111]
	v_mfma_f32_16x16x32_bf16 v[104:107], v[168:171], v[200:203], v[104:107]
	v_mfma_f32_16x16x32_bf16 v[92:95], v[148:151], v[208:211], v[92:95]
	v_mfma_f32_16x16x32_bf16 v[88:91], v[168:171], v[208:211], v[88:91]
	v_mfma_f32_16x16x32_bf16 v[76:79], v[148:151], v[216:219], v[76:79]
	v_mfma_f32_16x16x32_bf16 v[72:75], v[168:171], v[216:219], v[72:75]
	v_mfma_f32_16x16x32_bf16 v[124:127], v[164:167], v[196:199], v[124:127]
	v_mfma_f32_16x16x32_bf16 v[120:123], v[172:175], v[196:199], v[120:123]
	v_mfma_f32_16x16x32_bf16 v[108:111], v[164:167], v[204:207], v[108:111]
	v_mfma_f32_16x16x32_bf16 v[104:107], v[172:175], v[204:207], v[104:107]
	v_mfma_f32_16x16x32_bf16 v[92:95], v[164:167], v[212:215], v[92:95]
	v_mfma_f32_16x16x32_bf16 v[88:91], v[172:175], v[212:215], v[88:91]
	v_mfma_f32_16x16x32_bf16 v[76:79], v[164:167], v[222:225], v[76:79]
	v_mfma_f32_16x16x32_bf16 v[72:75], v[172:175], v[222:225], v[72:75]
	v_mfma_f32_16x16x32_bf16 v[116:119], v[176:179], v[192:195], v[116:119]
	v_mfma_f32_16x16x32_bf16 v[112:115], v[184:187], v[192:195], v[112:115]
	v_mfma_f32_16x16x32_bf16 v[100:103], v[176:179], v[200:203], v[100:103]
	v_mfma_f32_16x16x32_bf16 v[96:99], v[184:187], v[200:203], v[96:99]
	v_mfma_f32_16x16x32_bf16 v[84:87], v[176:179], v[208:211], v[84:87]
	v_mfma_f32_16x16x32_bf16 v[80:83], v[184:187], v[208:211], v[80:83]
	v_mfma_f32_16x16x32_bf16 v[68:71], v[176:179], v[216:219], v[68:71]
	v_mfma_f32_16x16x32_bf16 v[64:67], v[184:187], v[216:219], v[64:67]
	v_mfma_f32_16x16x32_bf16 v[116:119], v[180:183], v[196:199], v[116:119]
	v_mfma_f32_16x16x32_bf16 v[112:115], v[188:191], v[196:199], v[112:115]
	v_mfma_f32_16x16x32_bf16 v[100:103], v[180:183], v[204:207], v[100:103]
	v_mfma_f32_16x16x32_bf16 v[96:99], v[188:191], v[204:207], v[96:99]
	v_mfma_f32_16x16x32_bf16 v[84:87], v[180:183], v[212:215], v[84:87]
	v_mfma_f32_16x16x32_bf16 v[80:83], v[188:191], v[212:215], v[80:83]
	v_mfma_f32_16x16x32_bf16 v[68:71], v[180:183], v[222:225], v[68:71]
	v_mfma_f32_16x16x32_bf16 v[64:67], v[188:191], v[222:225], v[64:67]
	s_barrier
	s_setprio 0
	s_add_i32 s27, s77, s34
	v_lshl_add_u64 v[152:153], s[84:85], 0, v[130:131]
	s_mov_b32 m0, s27
	ds_read_b128 v[192:195], v162 offset:16384
	ds_read_b128 v[196:199], v252 offset:16384
	ds_read_b128 v[200:203], v162 offset:18432
	ds_read_b128 v[204:207], v252 offset:18432
	ds_read_b128 v[208:211], v162 offset:20480
	ds_read_b128 v[212:215], v252 offset:20480
	ds_read_b128 v[216:219], v162 offset:22528
	ds_read_b128 v[222:225], v252 offset:22528
	global_load_lds_dwordx4 v[152:153], off
	s_add_i32 m0, s27, 0x2000
	v_lshl_add_u64 v[226:227], s[84:85], 0, v[134:135]
	s_add_u32 s84, s84, s10
	s_addc_u32 s85, s85, s11
	s_add_i32 s27, s78, s34
	global_load_lds_dwordx4 v[226:227], off
	v_lshl_add_u64 v[228:229], s[84:85], 0, v[130:131]
	s_mov_b32 m0, s27
	v_lshl_add_u64 v[230:231], s[84:85], 0, v[134:135]
	global_load_lds_dwordx4 v[228:229], off
	s_add_i32 m0, s27, 0x2000
	v_lshl_add_u64 v[232:233], s[22:23], 0, v[128:129]
	global_load_lds_dwordx4 v[230:231], off
	s_mov_b32 m0, s35
	v_lshl_add_u64 v[234:235], s[22:23], 0, v[132:133]
	global_load_lds_dwordx4 v[232:233], off
	s_mov_b32 m0, s36
	s_nop 0
	global_load_lds_dwordx4 v[234:235], off
	s_waitcnt vmcnt(8)
	s_waitcnt lgkmcnt(0)
	s_setprio 1
	s_barrier
	v_mfma_f32_16x16x32_bf16 v[60:63], v[148:151], v[192:195], v[60:63]
	v_mfma_f32_16x16x32_bf16 v[56:59], v[168:171], v[192:195], v[56:59]
	v_mfma_f32_16x16x32_bf16 v[44:47], v[148:151], v[200:203], v[44:47]
	v_mfma_f32_16x16x32_bf16 v[40:43], v[168:171], v[200:203], v[40:43]
	v_mfma_f32_16x16x32_bf16 v[28:31], v[148:151], v[208:211], v[28:31]
	v_mfma_f32_16x16x32_bf16 v[24:27], v[168:171], v[208:211], v[24:27]
	v_mfma_f32_16x16x32_bf16 v[12:15], v[148:151], v[216:219], v[12:15]
	v_mfma_f32_16x16x32_bf16 v[8:11], v[168:171], v[216:219], v[8:11]
	v_mfma_f32_16x16x32_bf16 v[60:63], v[164:167], v[196:199], v[60:63]
	v_mfma_f32_16x16x32_bf16 v[56:59], v[172:175], v[196:199], v[56:59]
	v_mfma_f32_16x16x32_bf16 v[44:47], v[164:167], v[204:207], v[44:47]
	v_mfma_f32_16x16x32_bf16 v[40:43], v[172:175], v[204:207], v[40:43]
	v_mfma_f32_16x16x32_bf16 v[28:31], v[164:167], v[212:215], v[28:31]
	v_mfma_f32_16x16x32_bf16 v[24:27], v[172:175], v[212:215], v[24:27]
	v_mfma_f32_16x16x32_bf16 v[12:15], v[164:167], v[222:225], v[12:15]
	v_mfma_f32_16x16x32_bf16 v[8:11], v[172:175], v[222:225], v[8:11]
	v_mfma_f32_16x16x32_bf16 v[52:55], v[176:179], v[192:195], v[52:55]
	v_mfma_f32_16x16x32_bf16 v[48:51], v[184:187], v[192:195], v[48:51]
	v_mfma_f32_16x16x32_bf16 v[36:39], v[176:179], v[200:203], v[36:39]
	v_mfma_f32_16x16x32_bf16 v[32:35], v[184:187], v[200:203], v[32:35]
	v_mfma_f32_16x16x32_bf16 v[20:23], v[176:179], v[208:211], v[20:23]
	v_mfma_f32_16x16x32_bf16 v[16:19], v[184:187], v[208:211], v[16:19]
	v_mfma_f32_16x16x32_bf16 v[4:7], v[176:179], v[216:219], v[4:7]
	v_mfma_f32_16x16x32_bf16 v[0:3], v[184:187], v[216:219], v[0:3]
	v_mfma_f32_16x16x32_bf16 v[52:55], v[180:183], v[196:199], v[52:55]
	v_mfma_f32_16x16x32_bf16 v[48:51], v[188:191], v[196:199], v[48:51]
	v_mfma_f32_16x16x32_bf16 v[36:39], v[180:183], v[204:207], v[36:39]
	v_mfma_f32_16x16x32_bf16 v[32:35], v[188:191], v[204:207], v[32:35]
	v_mfma_f32_16x16x32_bf16 v[20:23], v[180:183], v[212:215], v[20:23]
	v_mfma_f32_16x16x32_bf16 v[16:19], v[188:191], v[212:215], v[16:19]
	v_mfma_f32_16x16x32_bf16 v[4:7], v[180:183], v[222:225], v[4:7]
	v_mfma_f32_16x16x32_bf16 v[0:3], v[188:191], v[222:225], v[0:3]
	s_barrier
	s_setprio 0
	s_add_i32 s27, 0, 0x18000
	v_add_u32_e32 v136, s27, v156
	s_add_i32 s81, 0, 0x1c000
	v_xor_b32_e32 v255, 64, v136
	ds_read_b128 v[148:151], v136
	ds_read_b128 v[164:167], v255
	ds_read_b128 v[168:171], v136 offset:2048
	ds_read_b128 v[172:175], v255 offset:2048
	v_add_u32_e32 v136, s81, v156
	v_xor_b32_e32 v255, 64, v136
	ds_read_b128 v[176:179], v136
	ds_read_b128 v[180:183], v255
	ds_read_b128 v[184:187], v136 offset:2048
	ds_read_b128 v[188:191], v255 offset:2048
	s_add_u32 s22, s22, s10
	s_addc_u32 s23, s23, s11
	s_mov_b32 m0, s37
	v_lshl_add_u64 v[236:237], s[22:23], 0, v[128:129]
	ds_read_b128 v[192:195], v162 offset:32768
	ds_read_b128 v[196:199], v252 offset:32768
	ds_read_b128 v[200:203], v162 offset:34816
	ds_read_b128 v[204:207], v252 offset:34816
	ds_read_b128 v[208:211], v162 offset:36864
	ds_read_b128 v[212:215], v252 offset:36864
	ds_read_b128 v[216:219], v162 offset:38912
	ds_read_b128 v[222:225], v252 offset:38912
	global_load_lds_dwordx4 v[236:237], off
	v_lshl_add_u64 v[236:237], s[22:23], 0, v[132:133]
	s_mov_b32 m0, s38
	s_nop 0
	global_load_lds_dwordx4 v[236:237], off
	s_waitcnt vmcnt(8)
	s_waitcnt lgkmcnt(0)
	s_setprio 1
	s_barrier
	v_mfma_f32_16x16x32_bf16 v[124:127], v[148:151], v[192:195], v[124:127]
	v_mfma_f32_16x16x32_bf16 v[120:123], v[168:171], v[192:195], v[120:123]
	v_mfma_f32_16x16x32_bf16 v[108:111], v[148:151], v[200:203], v[108:111]
	v_mfma_f32_16x16x32_bf16 v[104:107], v[168:171], v[200:203], v[104:107]
	v_mfma_f32_16x16x32_bf16 v[92:95], v[148:151], v[208:211], v[92:95]
	v_mfma_f32_16x16x32_bf16 v[88:91], v[168:171], v[208:211], v[88:91]
	v_mfma_f32_16x16x32_bf16 v[76:79], v[148:151], v[216:219], v[76:79]
	v_mfma_f32_16x16x32_bf16 v[72:75], v[168:171], v[216:219], v[72:75]
	v_mfma_f32_16x16x32_bf16 v[124:127], v[164:167], v[196:199], v[124:127]
	v_mfma_f32_16x16x32_bf16 v[120:123], v[172:175], v[196:199], v[120:123]
	v_mfma_f32_16x16x32_bf16 v[108:111], v[164:167], v[204:207], v[108:111]
	v_mfma_f32_16x16x32_bf16 v[104:107], v[172:175], v[204:207], v[104:107]
	v_mfma_f32_16x16x32_bf16 v[92:95], v[164:167], v[212:215], v[92:95]
	v_mfma_f32_16x16x32_bf16 v[88:91], v[172:175], v[212:215], v[88:91]
	v_mfma_f32_16x16x32_bf16 v[76:79], v[164:167], v[222:225], v[76:79]
	v_mfma_f32_16x16x32_bf16 v[72:75], v[172:175], v[222:225], v[72:75]
	v_mfma_f32_16x16x32_bf16 v[116:119], v[176:179], v[192:195], v[116:119]
	v_mfma_f32_16x16x32_bf16 v[112:115], v[184:187], v[192:195], v[112:115]
	v_mfma_f32_16x16x32_bf16 v[100:103], v[176:179], v[200:203], v[100:103]
	v_mfma_f32_16x16x32_bf16 v[96:99], v[184:187], v[200:203], v[96:99]
	v_mfma_f32_16x16x32_bf16 v[84:87], v[176:179], v[208:211], v[84:87]
	v_mfma_f32_16x16x32_bf16 v[80:83], v[184:187], v[208:211], v[80:83]
	v_mfma_f32_16x16x32_bf16 v[68:71], v[176:179], v[216:219], v[68:71]
	v_mfma_f32_16x16x32_bf16 v[64:67], v[184:187], v[216:219], v[64:67]
	v_mfma_f32_16x16x32_bf16 v[116:119], v[180:183], v[196:199], v[116:119]
	v_mfma_f32_16x16x32_bf16 v[112:115], v[188:191], v[196:199], v[112:115]
	v_mfma_f32_16x16x32_bf16 v[100:103], v[180:183], v[204:207], v[100:103]
	v_mfma_f32_16x16x32_bf16 v[96:99], v[188:191], v[204:207], v[96:99]
	v_mfma_f32_16x16x32_bf16 v[84:87], v[180:183], v[212:215], v[84:87]
	v_mfma_f32_16x16x32_bf16 v[80:83], v[188:191], v[212:215], v[80:83]
	v_mfma_f32_16x16x32_bf16 v[68:71], v[180:183], v[222:225], v[68:71]
	v_mfma_f32_16x16x32_bf16 v[64:67], v[188:191], v[222:225], v[64:67]
	s_barrier
	s_setprio 0
	s_add_i32 s22, s27, s34
	v_lshl_add_u64 v[152:153], v[152:153], 0, s[16:17]
	s_mov_b32 m0, s22
	ds_read_b128 v[192:195], v162 offset:49152
	ds_read_b128 v[196:199], v252 offset:49152
	ds_read_b128 v[200:203], v162 offset:51200
	ds_read_b128 v[204:207], v252 offset:51200
	ds_read_b128 v[208:211], v162 offset:53248
	ds_read_b128 v[212:215], v252 offset:53248
	ds_read_b128 v[216:219], v162 offset:55296
	ds_read_b128 v[222:225], v252 offset:55296
	global_load_lds_dwordx4 v[152:153], off
	v_lshl_add_u64 v[152:153], v[226:227], 0, s[16:17]
	s_add_i32 m0, s22, 0x2000
	s_add_i32 s22, s81, s34
	global_load_lds_dwordx4 v[152:153], off
	v_lshl_add_u64 v[152:153], v[228:229], 0, s[16:17]
	s_mov_b32 m0, s22
	s_nop 0
	global_load_lds_dwordx4 v[152:153], off
	v_lshl_add_u64 v[152:153], v[230:231], 0, s[16:17]
	s_add_i32 m0, s22, 0x2000
	s_nop 0
	global_load_lds_dwordx4 v[152:153], off
	v_lshl_add_u64 v[152:153], v[232:233], 0, s[16:17]
	s_mov_b32 m0, s40
	s_nop 0
	global_load_lds_dwordx4 v[152:153], off
	v_lshl_add_u64 v[152:153], v[234:235], 0, s[16:17]
	s_mov_b32 m0, s41
	s_nop 0
	global_load_lds_dwordx4 v[152:153], off
	s_waitcnt vmcnt(8)
	s_waitcnt lgkmcnt(0)
	s_setprio 1
	s_barrier
	v_mfma_f32_16x16x32_bf16 v[60:63], v[148:151], v[192:195], v[60:63]
	v_mfma_f32_16x16x32_bf16 v[56:59], v[168:171], v[192:195], v[56:59]
	v_mfma_f32_16x16x32_bf16 v[44:47], v[148:151], v[200:203], v[44:47]
	v_mfma_f32_16x16x32_bf16 v[40:43], v[168:171], v[200:203], v[40:43]
	v_mfma_f32_16x16x32_bf16 v[28:31], v[148:151], v[208:211], v[28:31]
	v_mfma_f32_16x16x32_bf16 v[24:27], v[168:171], v[208:211], v[24:27]
	v_mfma_f32_16x16x32_bf16 v[12:15], v[148:151], v[216:219], v[12:15]
	v_mfma_f32_16x16x32_bf16 v[8:11], v[168:171], v[216:219], v[8:11]
	v_mfma_f32_16x16x32_bf16 v[60:63], v[164:167], v[196:199], v[60:63]
	v_mfma_f32_16x16x32_bf16 v[56:59], v[172:175], v[196:199], v[56:59]
	v_mfma_f32_16x16x32_bf16 v[44:47], v[164:167], v[204:207], v[44:47]
	v_mfma_f32_16x16x32_bf16 v[40:43], v[172:175], v[204:207], v[40:43]
	v_mfma_f32_16x16x32_bf16 v[28:31], v[164:167], v[212:215], v[28:31]
	v_mfma_f32_16x16x32_bf16 v[24:27], v[172:175], v[212:215], v[24:27]
	v_mfma_f32_16x16x32_bf16 v[12:15], v[164:167], v[222:225], v[12:15]
	v_mfma_f32_16x16x32_bf16 v[8:11], v[172:175], v[222:225], v[8:11]
	v_mfma_f32_16x16x32_bf16 v[52:55], v[176:179], v[192:195], v[52:55]
	v_mfma_f32_16x16x32_bf16 v[48:51], v[184:187], v[192:195], v[48:51]
	v_mfma_f32_16x16x32_bf16 v[36:39], v[176:179], v[200:203], v[36:39]
	v_mfma_f32_16x16x32_bf16 v[32:35], v[184:187], v[200:203], v[32:35]
	v_mfma_f32_16x16x32_bf16 v[20:23], v[176:179], v[208:211], v[20:23]
	v_mfma_f32_16x16x32_bf16 v[16:19], v[184:187], v[208:211], v[16:19]
	v_mfma_f32_16x16x32_bf16 v[4:7], v[176:179], v[216:219], v[4:7]
	v_mfma_f32_16x16x32_bf16 v[0:3], v[184:187], v[216:219], v[0:3]
	v_mfma_f32_16x16x32_bf16 v[52:55], v[180:183], v[196:199], v[52:55]
	v_mfma_f32_16x16x32_bf16 v[48:51], v[188:191], v[196:199], v[48:51]
	v_mfma_f32_16x16x32_bf16 v[36:39], v[180:183], v[204:207], v[36:39]
	v_mfma_f32_16x16x32_bf16 v[32:35], v[188:191], v[204:207], v[32:35]
	v_mfma_f32_16x16x32_bf16 v[20:23], v[180:183], v[212:215], v[20:23]
	v_mfma_f32_16x16x32_bf16 v[16:19], v[188:191], v[212:215], v[16:19]
	v_mfma_f32_16x16x32_bf16 v[4:7], v[180:183], v[222:225], v[4:7]
	v_mfma_f32_16x16x32_bf16 v[0:3], v[188:191], v[222:225], v[0:3]
	s_barrier
	s_setprio 0
	s_add_u32 s8, s8, 0x100
	s_addc_u32 s9, s9, 0
	s_cmp_eq_u32 s93, 30
	s_cselect_b32 s94, 0x1000, 0
	s_sub_u32 s8, s8, s94
	s_subb_u32 s9, s9, 0
	s_add_i32 s93, s93, 2
	s_cmp_eq_u32 s93, 32
	s_cselect_b32 s93, 0, s93
	s_add_u32 s24, s24, 0x100
	s_addc_u32 s25, s25, 0
	s_cmp_eq_u32 s93, 30
	s_cselect_b32 s94, 0x1000, 0
	s_sub_u32 s24, s24, s94
	s_subb_u32 s25, s25, 0
	s_cmp_ge_i32 s26, s42
	s_mov_b32 s22, s26
	s_cbranch_scc0 .LBB0_310
